# phase 0 rebalanced: pool items moved to WGs 144-175, layer-0 weight conversion on WGs 176-255, silu(c) staging loads batched
# speedup vs baseline: 1.0327x; 1.0186x over previous
.LBB0_680:
	s_mov_b64 s[40:41], s[38:39]
	s_and_b64 vcc, exec, s[4:5]
	v_readlane_b32 s38, v253, 61
	v_readlane_b32 s39, v254, 54
	s_cbranch_vccz .Ldef_check
	v_mov_b32_e32 v84, v244
	s_nop 0
	v_readfirstlane_b32 s6, v84
	v_cmp_gt_i32_e32 vcc, s68, v84
	s_and_saveexec_b64 s[0:1], vcc
	s_cbranch_execz .LBB0_684
	v_readlane_b32 s4, v253, 49
	v_ashrrev_i32_e32 v85, 31, v84
	v_mov_b32_e32 v0, s4
	ds_read_b64 v[0:1], v0
	v_lshl_add_u32 v5, v84, 2, 0
	v_lshlrev_b64 v[2:3], 2, v[84:85]
	s_mov_b64 s[4:5], 0x1000
	s_waitcnt lgkmcnt(0)
	v_readfirstlane_b32 s9, v1
	v_readfirstlane_b32 s8, v0
	s_nop 3
	v_lshl_add_u64 v[6:7], s[8:9], 0, v[2:3]
	global_load_dword v8, v[6:7], off
	global_load_dword v9, v[6:7], off offset:2048
	v_lshl_add_u64 v[6:7], v[6:7], 0, s[4:5]
	global_load_dword v10, v[6:7], off
	global_load_dword v11, v[6:7], off offset:2048
	v_lshl_add_u64 v[6:7], v[6:7], 0, s[4:5]
	global_load_dword v12, v[6:7], off
	global_load_dword v13, v[6:7], off offset:2048
	v_lshl_add_u64 v[6:7], v[6:7], 0, s[4:5]
	global_load_dword v14, v[6:7], off
	global_load_dword v15, v[6:7], off offset:2048
	v_lshl_add_u64 v[6:7], v[6:7], 0, s[4:5]
	global_load_dword v16, v[6:7], off
	global_load_dword v17, v[6:7], off offset:2048
	v_lshl_add_u64 v[6:7], v[6:7], 0, s[4:5]
	global_load_dword v18, v[6:7], off
	global_load_dword v19, v[6:7], off offset:2048
	v_lshl_add_u64 v[6:7], v[6:7], 0, s[4:5]
	global_load_dword v20, v[6:7], off
	global_load_dword v21, v[6:7], off offset:2048
	v_lshl_add_u64 v[6:7], v[6:7], 0, s[4:5]
	global_load_dword v22, v[6:7], off
	global_load_dword v23, v[6:7], off offset:2048
	s_waitcnt vmcnt(0)
	v_mul_f32_e32 v24, 0xbfb8aa3b, v8
	v_mul_f32_e32 v25, 0xbfb8aa3b, v9
	v_mul_f32_e32 v26, 0xbfb8aa3b, v10
	v_mul_f32_e32 v27, 0xbfb8aa3b, v11
	v_mul_f32_e32 v28, 0xbfb8aa3b, v12
	v_mul_f32_e32 v29, 0xbfb8aa3b, v13
	v_mul_f32_e32 v30, 0xbfb8aa3b, v14
	v_mul_f32_e32 v31, 0xbfb8aa3b, v15
	v_mul_f32_e32 v32, 0xbfb8aa3b, v16
	v_mul_f32_e32 v33, 0xbfb8aa3b, v17
	v_mul_f32_e32 v34, 0xbfb8aa3b, v18
	v_mul_f32_e32 v35, 0xbfb8aa3b, v19
	v_mul_f32_e32 v36, 0xbfb8aa3b, v20
	v_mul_f32_e32 v37, 0xbfb8aa3b, v21
	v_mul_f32_e32 v38, 0xbfb8aa3b, v22
	v_mul_f32_e32 v39, 0xbfb8aa3b, v23
	v_exp_f32_e32 v24, v24
	v_exp_f32_e32 v25, v25
	v_exp_f32_e32 v26, v26
	v_exp_f32_e32 v27, v27
	v_exp_f32_e32 v28, v28
	v_exp_f32_e32 v29, v29
	v_exp_f32_e32 v30, v30
	v_exp_f32_e32 v31, v31
	v_exp_f32_e32 v32, v32
	v_exp_f32_e32 v33, v33
	v_exp_f32_e32 v34, v34
	v_exp_f32_e32 v35, v35
	v_exp_f32_e32 v36, v36
	v_exp_f32_e32 v37, v37
	v_exp_f32_e32 v38, v38
	v_exp_f32_e32 v39, v39
	v_add_f32_e32 v24, 1.0, v24
	v_add_f32_e32 v25, 1.0, v25
	v_add_f32_e32 v26, 1.0, v26
	v_add_f32_e32 v27, 1.0, v27
	v_add_f32_e32 v28, 1.0, v28
	v_add_f32_e32 v29, 1.0, v29
	v_add_f32_e32 v30, 1.0, v30
	v_add_f32_e32 v31, 1.0, v31
	v_add_f32_e32 v32, 1.0, v32
	v_add_f32_e32 v33, 1.0, v33
	v_add_f32_e32 v34, 1.0, v34
	v_add_f32_e32 v35, 1.0, v35
	v_add_f32_e32 v36, 1.0, v36
	v_add_f32_e32 v37, 1.0, v37
	v_add_f32_e32 v38, 1.0, v38
	v_add_f32_e32 v39, 1.0, v39
	v_rcp_f32_e32 v24, v24
	v_rcp_f32_e32 v25, v25
	v_rcp_f32_e32 v26, v26
	v_rcp_f32_e32 v27, v27
	v_rcp_f32_e32 v28, v28
	v_rcp_f32_e32 v29, v29
	v_rcp_f32_e32 v30, v30
	v_rcp_f32_e32 v31, v31
	v_rcp_f32_e32 v32, v32
	v_rcp_f32_e32 v33, v33
	v_rcp_f32_e32 v34, v34
	v_rcp_f32_e32 v35, v35
	v_rcp_f32_e32 v36, v36
	v_rcp_f32_e32 v37, v37
	v_rcp_f32_e32 v38, v38
	v_rcp_f32_e32 v39, v39
	v_mul_f32_e32 v8, v8, v24
	v_mul_f32_e32 v9, v9, v25
	v_mul_f32_e32 v10, v10, v26
	v_mul_f32_e32 v11, v11, v27
	v_mul_f32_e32 v12, v12, v28
	v_mul_f32_e32 v13, v13, v29
	v_mul_f32_e32 v14, v14, v30
	v_mul_f32_e32 v15, v15, v31
	v_mul_f32_e32 v16, v16, v32
	v_mul_f32_e32 v17, v17, v33
	v_mul_f32_e32 v18, v18, v34
	v_mul_f32_e32 v19, v19, v35
	v_mul_f32_e32 v20, v20, v36
	v_mul_f32_e32 v21, v21, v37
	v_mul_f32_e32 v22, v22, v38
	v_mul_f32_e32 v23, v23, v39
	ds_write_b32 v5, v8 offset:0
	ds_write_b32 v5, v9 offset:2048
	ds_write_b32 v5, v10 offset:4096
	ds_write_b32 v5, v11 offset:6144
	ds_write_b32 v5, v12 offset:8192
	ds_write_b32 v5, v13 offset:10240
	ds_write_b32 v5, v14 offset:12288
	ds_write_b32 v5, v15 offset:14336
	ds_write_b32 v5, v16 offset:16384
	ds_write_b32 v5, v17 offset:18432
	ds_write_b32 v5, v18 offset:20480
	ds_write_b32 v5, v19 offset:22528
	ds_write_b32 v5, v20 offset:24576
	ds_write_b32 v5, v21 offset:26624
	ds_write_b32 v5, v22 offset:28672
	ds_write_b32 v5, v23 offset:30720

.LBB0_692:
	s_or_b64 exec, exec, s[4:5]
	s_lshl_b32 s0, s52, 3
	s_add_i32 s17, s16, s0
	s_add_i32 s8, s17, 0xfffffb80
	s_cmp_gt_u32 s8, 0xff
	s_cbranch_scc1 .LBB0_697
	v_readlane_b32 s0, v253, 55
	s_nop 0
	v_mov_b32_e32 v0, s0
	v_readlane_b32 s0, v253, 56
	s_nop 1
	v_mov_b32_e32 v4, s0
	ds_read_b128 v[0:3], v0
	ds_read_b64 v[86:87], v4

.LBB0_697:
	s_movk_i32 s98, 0x3100
	s_add_i32 s17, s17, 0xfffffa80
	s_movk_i32 s64, 0x280
	s_cmp_lt_i32 s17, 0
	s_cselect_b32 s17, s98, s17

.LBB0_743:
	v_readlane_b32 s64, v254, 28
	v_readlane_b32 s28, v254, 10
	v_readlane_b32 s30, v254, 12
	v_readlane_b32 s34, v254, 14
	v_readlane_b32 s36, v254, 16
	v_readlane_b32 s24, v254, 18
	v_readlane_b32 s16, v254, 20
	v_readlane_b32 s18, v254, 22
	v_readlane_b32 s20, v254, 24
	v_readlane_b32 s22, v254, 26
	s_mov_b64 s[0:1], 0
	v_readlane_b32 s29, v254, 11
	v_readlane_b32 s31, v254, 13
	v_readlane_b32 s26, v254, 29
	v_readlane_b32 s35, v254, 15
	v_readlane_b32 s37, v254, 17
	v_readlane_b32 s25, v254, 19
	v_readlane_b32 s17, v254, 21
	v_readlane_b32 s19, v254, 23
	v_readlane_b32 s21, v254, 25
	v_readlane_b32 s23, v254, 27
	s_mov_b64 s[38:39], s[40:41]
